# grid barrier: XCD leaders no longer bump the (now unused) per-XCD relay word, so they leave the barrier without waiting for that atomic
# speedup vs baseline: 1.0038x; 1.0038x over previous
; __device__ __forceinline__ unsigned xb_add(unsigned* p, unsigned v) { return __hip_atomic_fetch_add(p, v, __ATOMIC_RELAXED, __HIP_MEMORY_SCOPE_AGENT); }
; __device__ __forceinline__ void xcd_barrier(const XcdBarrier& b) {
;     ...
;             __builtin_amdgcn_fence(__ATOMIC_ACQUIRE, "agent");
;             xb_add(&bar[XB_XGEN(b.x)], 1u);
;             asm volatile("s_waitcnt vmcnt(0)" ::: "memory");
.LBB0_193:
	s_or_b64 exec, exec, s[6:7]
	s_mov_b64 s[6:7], exec
	v_mbcnt_lo_u32_b32 v0, s6, 0
	v_mbcnt_hi_u32_b32 v0, s7, v0
	v_cmp_eq_u32_e32 vcc, 0, v0
	s_waitcnt vmcnt(0)
	buffer_inv sc1
	s_and_saveexec_b64 s[12:13], vcc
	s_cbranch_execz .LBB0_195
	s_bcnt1_i32_b64 s0, s[6:7]
	v_mov_b32_e32 v0, 0x2000
	v_mov_b32_e32 v1, s0
	s_nop 0

; __device__ __forceinline__ unsigned xb_add(unsigned* p, unsigned v) { return __hip_atomic_fetch_add(p, v, __ATOMIC_RELAXED, __HIP_MEMORY_SCOPE_AGENT); }
; __device__ __forceinline__ void xcd_barrier(const XcdBarrier& b) {
;     ...
;             __builtin_amdgcn_fence(__ATOMIC_ACQUIRE, "agent");
;             xb_add(&bar[XB_XGEN(b.x)], 1u);
;             asm volatile("s_waitcnt vmcnt(0)" ::: "memory");
.LBB0_274:
	s_or_b64 exec, exec, s[8:9]
	s_mov_b64 s[8:9], exec
	v_mbcnt_lo_u32_b32 v0, s8, 0
	v_mbcnt_hi_u32_b32 v0, s9, v0
	v_cmp_eq_u32_e32 vcc, 0, v0
	s_waitcnt vmcnt(0)
	buffer_inv sc1
	s_and_saveexec_b64 s[14:15], vcc
	s_cbranch_execz .LBB0_276
	s_bcnt1_i32_b64 s0, s[8:9]
	v_mov_b32_e32 v0, 0x2000
	v_mov_b32_e32 v1, s0
	s_nop 0

; __device__ __forceinline__ unsigned xb_add(unsigned* p, unsigned v) { return __hip_atomic_fetch_add(p, v, __ATOMIC_RELAXED, __HIP_MEMORY_SCOPE_AGENT); }
; __device__ __forceinline__ void xcd_barrier(const XcdBarrier& b) {
;     ...
;             __builtin_amdgcn_fence(__ATOMIC_ACQUIRE, "agent");
;             xb_add(&bar[XB_XGEN(b.x)], 1u);
;             asm volatile("s_waitcnt vmcnt(0)" ::: "memory");
.LBB0_471:
	s_or_b64 exec, exec, s[10:11]
	s_mov_b64 s[10:11], exec
	v_mbcnt_lo_u32_b32 v0, s10, 0
	v_mbcnt_hi_u32_b32 v0, s11, v0
	v_cmp_eq_u32_e32 vcc, 0, v0
	s_waitcnt vmcnt(0)
	buffer_inv sc1
	s_and_saveexec_b64 s[14:15], vcc
	s_cbranch_execz .LBB0_473
	s_bcnt1_i32_b64 s0, s[10:11]
	v_mov_b32_e32 v0, 0x2000
	v_mov_b32_e32 v1, s0
	s_nop 0

; __device__ __forceinline__ unsigned xb_add(unsigned* p, unsigned v) { return __hip_atomic_fetch_add(p, v, __ATOMIC_RELAXED, __HIP_MEMORY_SCOPE_AGENT); }
; __device__ __forceinline__ void xcd_barrier(const XcdBarrier& b) {
;     ...
;             __builtin_amdgcn_fence(__ATOMIC_ACQUIRE, "agent");
;             xb_add(&bar[XB_XGEN(b.x)], 1u);
;             asm volatile("s_waitcnt vmcnt(0)" ::: "memory");
.LBB0_653:
	s_or_b64 exec, exec, s[12:13]
	s_mov_b64 s[12:13], exec
	v_mbcnt_lo_u32_b32 v0, s12, 0
	v_mbcnt_hi_u32_b32 v0, s13, v0
	v_cmp_eq_u32_e32 vcc, 0, v0
	s_waitcnt vmcnt(0)
	buffer_inv sc1
	s_and_saveexec_b64 s[16:17], vcc
	s_cbranch_execz .LBB0_655
	s_bcnt1_i32_b64 s0, s[12:13]
	v_mov_b32_e32 v0, 0x2000
	v_mov_b32_e32 v1, s0
	s_nop 0

; __device__ __forceinline__ unsigned xb_add(unsigned* p, unsigned v) { return __hip_atomic_fetch_add(p, v, __ATOMIC_RELAXED, __HIP_MEMORY_SCOPE_AGENT); }
; __device__ __forceinline__ void xcd_barrier(const XcdBarrier& b) {
;     ...
;             __builtin_amdgcn_fence(__ATOMIC_ACQUIRE, "agent");
;             xb_add(&bar[XB_XGEN(b.x)], 1u);
;             asm volatile("s_waitcnt vmcnt(0)" ::: "memory");
.LBB0_1269:
	s_or_b64 exec, exec, s[8:9]
	s_mov_b64 s[8:9], exec
	v_mbcnt_lo_u32_b32 v0, s8, 0
	v_mbcnt_hi_u32_b32 v0, s9, v0
	v_cmp_eq_u32_e32 vcc, 0, v0
	s_waitcnt vmcnt(0)
	buffer_inv sc1
	s_and_saveexec_b64 s[12:13], vcc
	s_cbranch_execz .LBB0_1271
	s_bcnt1_i32_b64 s0, s[8:9]
	v_mov_b32_e32 v0, 0x2000
	v_mov_b32_e32 v1, s0
	s_nop 0
